# v43 + attention loop second half: packed v_pk_add/v_pk_fma f32 split into scalar ops, abs via source modifier instead of v_and
# speedup vs baseline: 1.0097x; 1.0046x over previous
; #define SBAR() __builtin_amdgcn_sched_barrier(0)
; template <int OFF> __device__ __forceinline__ s16x4 tr_read(int vb) { s16x4 r; asm volatile("ds_read_b64_tr_b16 %0, %1 offset:%2" : "=&v"(r) : "v"(vb), "i"(OFF) : "memory"); return r; }
; __device__ __forceinline__ void partialSM(f32x16& p0, f32x16& p1, float& m_reg, float& mn, float& alpha, float dq, float slope2, int hi) {
;     const float d0 = dq - (float)(4 * hi);
; #pragma unroll
;     for (int r = 0; r < 16; ++r) { const float c = (float)((r & 3) + 8 * (r >> 2)); p0[r] = fmaf(-slope2, fabsf(d0 - c), p0[r]); p1[r] = fmaf(-slope2, fabsf(d0 - c - 32.0f), p1[r]); }
;     float pmax = p0[0];
; #pragma unroll
;     for (int r = 1; r < 16; ++r) pmax = fmaxf(pmax, p0[r]);
; #pragma unroll
;     for (int r = 0; r < 16; ++r) pmax = fmaxf(pmax, p1[r]);
;     { auto rr = __builtin_amdgcn_permlane32_swap(__float_as_uint(pmax), __float_as_uint(pmax), false, false); pmax = fmaxf(__uint_as_float(rr[0]), __uint_as_float(rr[1])); }
;     if (__builtin_expect(__all(pmax - m_reg <= THR), 1)) { mn = m_reg; alpha = 1.f; }
;     else { mn = fmaxf(m_reg, pmax); alpha = __builtin_amdgcn_exp2f(m_reg - mn); m_reg = mn; }
; #pragma unroll
;     for (int r = 0; r < 16; ++r) { p0[r] = p0[r] - mn; p1[r] = p1[r] - mn; }
; #pragma unroll
;     for (int r = 0; r < 16; ++r) p0[r] = __builtin_amdgcn_exp2f(p0[r]);
; }
; template <int D0> __device__ __forceinline__ void pv_one(f32x16& od, int vb, bf16x8 pa0, bf16x8 pa1, bf16x8 pa2, bf16x8 pa3) {
;     const s16x4 l0 = tr_read<v_rd_off(D0, 0, 0)>(vb), h0 = tr_read<v_rd_off(D0, 0, 1)>(vb), l1 = tr_read<v_rd_off(D0, 1, 0)>(vb), h1 = tr_read<v_rd_off(D0, 1, 1)>(vb);
;     const s16x4 l2 = tr_read<v_rd_off(D0, 2, 0)>(vb), h2 = tr_read<v_rd_off(D0, 2, 1)>(vb), l3 = tr_read<v_rd_off(D0, 3, 0)>(vb), h3 = tr_read<v_rd_off(D0, 3, 1)>(vb);
;     asm volatile("s_waitcnt lgkmcnt(0)" ::: "memory"); SBAR();
;     ...
;     od = __builtin_amdgcn_mfma_f32_32x32x16_bf16(pa0, PK(l0, h0), od, 0, 0, 0);
;     od = __builtin_amdgcn_mfma_f32_32x32x16_bf16(pa1, PK(l1, h1), od, 0, 0, 0);
;     od = __builtin_amdgcn_mfma_f32_32x32x16_bf16(pa2, PK(l2, h2), od, 0, 0, 0);
;     od = __builtin_amdgcn_mfma_f32_32x32x16_bf16(pa3, PK(l3, h3), od, 0, 0, 0);
.LBB0_164:
	s_or_b64 exec, exec, s[10:11]
	ds_read_b64_tr_b16 v[178:179], v224 offset:0
	ds_read_b64_tr_b16 v[180:181], v224 offset:0x800
	ds_read_b64_tr_b16 v[234:235], v224 offset:0x1000
	ds_read_b64_tr_b16 v[236:237], v224 offset:0x1800
	ds_read_b64_tr_b16 v[238:239], v224 offset:0x2000
	ds_read_b64_tr_b16 v[240:241], v224 offset:0x2800
	ds_read_b64_tr_b16 v[242:243], v224 offset:0x3000
	ds_read_b64_tr_b16 v[244:245], v224 offset:0x3800
	s_waitcnt lgkmcnt(0)
	s_nop 0
	v_mfma_f32_32x32x16_bf16 v[48:63], v[96:99], v[178:181], v[48:63]
	ds_read_b64_tr_b16 v[178:179], v224 offset:0x200
	ds_read_b64_tr_b16 v[180:181], v224 offset:0xa00
	v_mfma_f32_32x32x16_bf16 v[48:63], v[100:103], v[234:237], v[48:63]
	ds_read_b64_tr_b16 v[234:235], v224 offset:0x1200
	ds_read_b64_tr_b16 v[236:237], v224 offset:0x1a00
	v_mfma_f32_32x32x16_bf16 v[48:63], v[104:107], v[238:241], v[48:63]
	ds_read_b64_tr_b16 v[238:239], v224 offset:0x2200
	ds_read_b64_tr_b16 v[240:241], v224 offset:0x2a00
	v_mfma_f32_32x32x16_bf16 v[48:63], v[108:111], v[242:245], v[48:63]
	ds_read_b64_tr_b16 v[242:243], v224 offset:0x3200
	ds_read_b64_tr_b16 v[244:245], v224 offset:0x3a00
	s_waitcnt lgkmcnt(0)
	v_mfma_f32_32x32x16_bf16 v[32:47], v[96:99], v[178:181], v[32:47]
	ds_read_b64_tr_b16 v[178:179], v224 offset:0x400
	ds_read_b64_tr_b16 v[180:181], v224 offset:0xc00
	v_mfma_f32_32x32x16_bf16 v[32:47], v[100:103], v[234:237], v[32:47]
	ds_read_b64_tr_b16 v[234:235], v224 offset:0x1400
	ds_read_b64_tr_b16 v[236:237], v224 offset:0x1c00
	v_mfma_f32_32x32x16_bf16 v[32:47], v[104:107], v[238:241], v[32:47]
	ds_read_b64_tr_b16 v[238:239], v224 offset:0x2400
	ds_read_b64_tr_b16 v[240:241], v224 offset:0x2c00
	v_mfma_f32_32x32x16_bf16 v[32:47], v[108:111], v[242:245], v[32:47]
	ds_read_b64_tr_b16 v[242:243], v224 offset:0x3400
	ds_read_b64_tr_b16 v[244:245], v224 offset:0x3c00
	s_waitcnt lgkmcnt(0)
	v_mfma_f32_32x32x16_bf16 v[16:31], v[96:99], v[178:181], v[16:31]
	ds_read_b64_tr_b16 v[178:179], v224 offset:0x600
	ds_read_b64_tr_b16 v[180:181], v224 offset:0xe00
	v_mfma_f32_32x32x16_bf16 v[16:31], v[100:103], v[234:237], v[16:31]
	ds_read_b64_tr_b16 v[234:235], v224 offset:0x1600
	ds_read_b64_tr_b16 v[236:237], v224 offset:0x1e00
	v_mfma_f32_32x32x16_bf16 v[16:31], v[104:107], v[238:241], v[16:31]
	ds_read_b64_tr_b16 v[238:239], v224 offset:0x2600
	ds_read_b64_tr_b16 v[240:241], v224 offset:0x2e00
	v_mfma_f32_32x32x16_bf16 v[16:31], v[108:111], v[242:245], v[16:31]
	ds_read_b64_tr_b16 v[242:243], v224 offset:0x3600
	ds_read_b64_tr_b16 v[244:245], v224 offset:0x3e00
	s_waitcnt lgkmcnt(0)
	v_mfma_f32_32x32x16_bf16 v[0:15], v[96:99], v[178:181], v[0:15]
	v_cvt_f32_u32_e32 v96, s2
	s_barrier
	v_sub_f32_e32 v96, v208, v96
	s_waitcnt vmcnt(3)
	s_waitcnt vmcnt(2)
	ds_write_b128 v219, v[142:145] offset:16384
	s_waitcnt vmcnt(1)
	ds_write_b128 v220, v[146:149] offset:16384
	s_waitcnt vmcnt(0)
	ds_write_b128 v221, v[150:153] offset:40960
	v_mfma_f32_32x32x16_bf16 v[0:15], v[100:103], v[234:237], v[0:15]
	v_mfma_f32_32x32x16_bf16 v[0:15], v[104:107], v[238:241], v[0:15]
	v_sub_f32_e32 v106, v96, v209
	v_add_f32_e32 v107, -1.0, v106
	v_fma_f32 v96, -v170, |v106|, v80
	v_fma_f32 v97, -v170, |v107|, v81
	v_add_f32_e64 v80, v106, s72
	v_add_f32_e64 v81, v107, s72
	v_max_f32_e32 v100, v96, v97
	v_fma_f32 v80, v172, |v80|, v64
	v_fma_f32 v81, v173, |v81|, v65
	v_add_f32_e64 v64, v106, s38
	v_add_f32_e64 v65, v106, s39
	v_fma_f32 v98, -v170, |v64|, v82
	v_fma_f32 v99, -v170, |v65|, v83
	v_add_f32_e64 v64, v64, s72
	v_add_f32_e64 v65, v65, s72
	v_mfma_f32_32x32x16_bf16 v[0:15], v[108:111], v[242:245], v[0:15]
	v_fma_f32 v82, v172, |v64|, v66
	v_fma_f32 v83, v173, |v65|, v67
	v_add_f32_e64 v64, v106, s30
	v_add_f32_e64 v65, v106, s31
	v_max3_f32 v66, v100, v98, v99
	v_fma_f32 v100, -v170, |v64|, v84
	v_fma_f32 v101, -v170, |v65|, v85
	v_add_f32_e64 v64, v64, s72
	v_add_f32_e64 v65, v65, s72
	v_max3_f32 v66, v66, v100, v101
	v_fma_f32 v84, v172, |v64|, v68
	v_fma_f32 v85, v173, |v65|, v69
	v_add_f32_e64 v64, v106, s62
	v_add_f32_e64 v65, v106, s63
	v_fma_f32 v102, -v170, |v64|, v86
	v_fma_f32 v103, -v170, |v65|, v87
	v_add_f32_e64 v64, v64, s72
	v_add_f32_e64 v65, v65, s72
	v_max3_f32 v66, v66, v102, v103
	v_fma_f32 v86, v172, |v64|, v70
	v_fma_f32 v87, v173, |v65|, v71
	v_add_f32_e64 v64, v106, s40
	v_add_f32_e64 v65, v106, s41
	v_fma_f32 v104, -v170, |v64|, v88
	v_fma_f32 v89, -v170, |v65|, v89
	v_add_f32_e64 v64, v64, s72
	v_add_f32_e64 v65, v65, s72
	v_max3_f32 v66, v66, v104, v89
	v_fma_f32 v70, v172, |v64|, v72
	v_fma_f32 v71, v173, |v65|, v73
	v_add_f32_e64 v64, v106, s42
	v_add_f32_e64 v65, v106, s43
	v_fma_f32 v72, -v170, |v64|, v90
	v_fma_f32 v73, -v170, |v65|, v91
	v_add_f32_e64 v64, v64, s72
	v_add_f32_e64 v65, v65, s72
	v_max3_f32 v88, v66, v72, v73
	v_fma_f32 v68, v172, |v64|, v74
	v_fma_f32 v69, v173, |v65|, v75
	v_add_f32_e64 v64, v106, s44
	v_add_f32_e64 v65, v106, s45
	v_fma_f32 v74, -v170, |v64|, v92
	v_fma_f32 v75, -v170, |v65|, v93
	v_add_f32_e64 v64, v64, s72
	v_add_f32_e64 v65, v65, s72
	v_max3_f32 v88, v88, v74, v75
	v_fma_f32 v66, v172, |v64|, v76
	v_fma_f32 v67, v173, |v65|, v77
	v_add_f32_e64 v64, v106, s48
	v_add_f32_e64 v65, v106, s49
	v_fma_f32 v76, -v170, |v64|, v94
	v_fma_f32 v77, -v170, |v65|, v95
	v_add_f32_e64 v64, v64, s72
	v_add_f32_e64 v65, v65, s72
	s_nop 0
	v_fma_f32 v64, v172, |v64|, v78
	v_fma_f32 v65, v173, |v65|, v79
	v_max3_f32 v78, v88, v76, v77
	v_max3_f32 v78, v78, v80, v81
	v_max3_f32 v78, v78, v82, v83
	v_max3_f32 v78, v78, v84, v85
	v_max3_f32 v78, v78, v86, v87
	v_max3_f32 v78, v78, v70, v71
	v_max3_f32 v78, v78, v68, v69
	v_max3_f32 v78, v78, v66, v67
	v_max3_f32 v78, v78, v64, v65
	v_mov_b32_e32 v79, v78
	s_nop 1
	v_permlane32_swap_b32_e32 v78, v79
	v_max_f32_e32 v79, v79, v79
	v_max_f32_e32 v78, v78, v78
	v_max_f32_e32 v78, v78, v79
	v_sub_f32_e32 v79, v78, v223
	v_cmp_ge_f32_e32 vcc, s68, v79
	v_max_f32_e32 v79, v223, v223
	v_max_f32_e32 v78, v79, v78
	v_sub_f32_e32 v79, v223, v78
	v_exp_f32_e32 v79, v79
	s_cmp_eq_u64 vcc, exec
	s_cselect_b64 s[10:11], -1, 0
	v_cndmask_b32_e64 v88, v79, 1.0, s[10:11]
	v_cmp_gt_f32_e32 vcc, 1.0, v88
	s_cbranch_vccz .LBB0_157
	s_and_saveexec_b64 s[22:23], s[6:7]
	s_cbranch_execz .LBB0_156
	ds_write_b32 v212, v88 offset:49280
	s_branch .LBB0_156
